# scan1: s_setprio 2 around each step's four f32 MFMAs
# baseline (speedup 1.0000x reference)
; template <int NV, bool WITH_Y, int CH>
; __device__ __forceinline__ void scan_run(f32x2 (&S)[4][8], const unsigned char* oh  , LAS float* wl, float* yout  , int lane) {
;     ...
;         for (int s = 0; s < CH; ++s) {
;             const LAS float* sp = wl + s * 384 + cs16;
;             f32x4 a4[4], w4[4], b4[4], k4[4], r4[4], v4 = {0.f, 0.f, 0.f, 0.f};
; #pragma unroll
;             for (int q = 0; q < 4; ++q) a4[q] = *(const LAS f32x4*)(sp + q * 4);
; #pragma unroll
;             for (int q = 0; q < 4; ++q) { w4[q] = *(const LAS f32x4*)(sp + 64 + q * 4); b4[q] = *(const LAS f32x4*)(sp + 128 + q * 4); }
;             if (NV >= 5) {
; #pragma unroll
;                 for (int q = 0; q < 4; ++q) k4[q] = *(const LAS f32x4*)(sp + 192 + q * 4);
;                 v4 = *(const LAS f32x4*)(wl + s * 384 + 256 + rg4);
;             }
;             if (WITH_Y) {
; #pragma unroll
;                 for (int q = 0; q < 4; ++q) r4[q] = *(const LAS f32x4*)(sp + 320 + q * 4);
;             }
;             __builtin_amdgcn_sched_barrier(0);
;             float sa[4];
; #pragma unroll
;             for (int r = 0; r < 4; ++r) {
;                 f32x2 e0 = S[r][0] * (f32x2){a4[0][0], a4[0][1]}, e1 = S[r][1] * (f32x2){a4[0][2], a4[0][3]};
; #pragma unroll
;                 for (int q = 1; q < 4; ++q) { e0 += S[r][2 * q] * (f32x2){a4[q][0], a4[q][1]}; e1 += S[r][2 * q + 1] * (f32x2){a4[q][2], a4[q][3]}; }
;                 sa[r] = quad_allsum((e0[0] + e0[1]) + (e1[0] + e1[1]));
;             }
; #pragma unroll
;             for (int q = 0; q < 4; ++q) {
;                 const f32x2 wlo = {w4[q][0], w4[q][1]}, whi = {w4[q][2], w4[q][3]}, blo = {b4[q][0], b4[q][1]}, bhi = {b4[q][2], b4[q][3]};
;                 if (NV >= 5) {
;                     const f32x2 klo = {k4[q][0], k4[q][1]}, khi = {k4[q][2], k4[q][3]};
; #pragma unroll
;                     for (int r = 0; r < 4; ++r) {
;                         const f32x2 sa2 = {sa[r], sa[r]}, vi2 = {v4[r], v4[r]};
;                         S[r][2 * q] = S[r][2 * q] * wlo + (blo * sa2 + klo * vi2);
;                         S[r][2 * q + 1] = S[r][2 * q + 1] * whi + (bhi * sa2 + khi * vi2);
;                     }
;                 } else {
; #pragma unroll
;                     for (int r = 0; r < 4; ++r) {
;                         const f32x2 sa2 = {sa[r], sa[r]};
;                         S[r][2 * q] = S[r][2 * q] * wlo + blo * sa2;
.Lscan_noload:
	ds_read_b128 v[64:67], v7 offset:0
	ds_read_b128 v[56:59], v7 offset:256
	ds_read_b128 v[68:71], v7 offset:32
	ds_read_b128 v[60:63], v7 offset:288
	ds_read_b128 v[72:75], v7 offset:64
	ds_read_b128 v[212:215], v7 offset:320
	ds_read_b128 v[76:79], v7 offset:96
	ds_read_b128 v[216:219], v7 offset:352
	ds_read_b128 v[80:83], v7 offset:128
	ds_read_b128 v[220:223], v7 offset:384
	ds_read_b128 v[84:87], v7 offset:160
	ds_read_b128 v[224:227], v7 offset:416
	ds_read_b128 v[88:91], v7 offset:192
	ds_read_b128 v[228:231], v7 offset:448
	ds_read_b128 v[92:95], v7 offset:224
	ds_read_b128 v[232:235], v7 offset:480
	ds_read_b32 v38, v8 offset:512
	ds_read_b32 v39, v8 offset:640
	ds_read_b32 v36, v9 offset:1024
	s_waitcnt lgkmcnt(0)
	v_pk_mul_f32 v[42:43], v[128:129], v[64:65]
	v_pk_mul_f32 v[128:129], v[128:129], v[56:57]
	v_pk_mul_f32 v[44:45], v[144:145], v[64:65]
	v_pk_mul_f32 v[144:145], v[144:145], v[56:57]
	v_pk_fma_f32 v[42:43], v[130:131], v[66:67], v[42:43]
	v_pk_mul_f32 v[130:131], v[130:131], v[58:59]
	v_pk_fma_f32 v[44:45], v[146:147], v[66:67], v[44:45]
	v_pk_mul_f32 v[146:147], v[146:147], v[58:59]
	v_pk_fma_f32 v[42:43], v[132:133], v[68:69], v[42:43]
	v_pk_mul_f32 v[132:133], v[132:133], v[60:61]
	v_pk_fma_f32 v[44:45], v[148:149], v[68:69], v[44:45]
	v_pk_mul_f32 v[148:149], v[148:149], v[60:61]
	v_pk_fma_f32 v[42:43], v[134:135], v[70:71], v[42:43]
	v_pk_mul_f32 v[134:135], v[134:135], v[62:63]
	v_pk_fma_f32 v[44:45], v[150:151], v[70:71], v[44:45]
	v_pk_mul_f32 v[150:151], v[150:151], v[62:63]
	v_pk_fma_f32 v[42:43], v[136:137], v[72:73], v[42:43]
	v_pk_mul_f32 v[136:137], v[136:137], v[212:213]
	v_pk_fma_f32 v[44:45], v[152:153], v[72:73], v[44:45]
	v_pk_mul_f32 v[152:153], v[152:153], v[212:213]
	v_pk_fma_f32 v[42:43], v[138:139], v[74:75], v[42:43]
	v_pk_mul_f32 v[138:139], v[138:139], v[214:215]
	v_pk_fma_f32 v[44:45], v[154:155], v[74:75], v[44:45]
	v_pk_mul_f32 v[154:155], v[154:155], v[214:215]
	v_pk_fma_f32 v[42:43], v[140:141], v[76:77], v[42:43]
	v_pk_mul_f32 v[140:141], v[140:141], v[216:217]
	v_pk_fma_f32 v[44:45], v[156:157], v[76:77], v[44:45]
	v_pk_mul_f32 v[156:157], v[156:157], v[216:217]
	v_pk_fma_f32 v[42:43], v[142:143], v[78:79], v[42:43]
	v_pk_mul_f32 v[142:143], v[142:143], v[218:219]
	v_pk_fma_f32 v[44:45], v[158:159], v[78:79], v[44:45]
	v_pk_mul_f32 v[158:159], v[158:159], v[218:219]
	v_pk_fma_f32 v[42:43], v[160:161], v[80:81], v[42:43]
	v_pk_mul_f32 v[160:161], v[160:161], v[220:221]
	v_pk_fma_f32 v[44:45], v[176:177], v[80:81], v[44:45]
	v_pk_mul_f32 v[176:177], v[176:177], v[220:221]
	v_pk_fma_f32 v[42:43], v[162:163], v[82:83], v[42:43]
	v_pk_mul_f32 v[162:163], v[162:163], v[222:223]
	v_pk_fma_f32 v[44:45], v[178:179], v[82:83], v[44:45]
	v_pk_mul_f32 v[178:179], v[178:179], v[222:223]
	v_pk_fma_f32 v[42:43], v[164:165], v[84:85], v[42:43]
	v_pk_mul_f32 v[164:165], v[164:165], v[224:225]
	v_pk_fma_f32 v[44:45], v[180:181], v[84:85], v[44:45]
	v_pk_mul_f32 v[180:181], v[180:181], v[224:225]
	v_pk_fma_f32 v[42:43], v[166:167], v[86:87], v[42:43]
	v_pk_mul_f32 v[166:167], v[166:167], v[226:227]
	v_pk_fma_f32 v[44:45], v[182:183], v[86:87], v[44:45]
	v_pk_mul_f32 v[182:183], v[182:183], v[226:227]
	v_pk_fma_f32 v[42:43], v[168:169], v[88:89], v[42:43]
	v_pk_mul_f32 v[168:169], v[168:169], v[228:229]
	v_pk_fma_f32 v[44:45], v[184:185], v[88:89], v[44:45]
	v_pk_mul_f32 v[184:185], v[184:185], v[228:229]
	v_pk_fma_f32 v[42:43], v[170:171], v[90:91], v[42:43]
	v_pk_mul_f32 v[170:171], v[170:171], v[230:231]
	v_pk_fma_f32 v[44:45], v[186:187], v[90:91], v[44:45]
	v_pk_mul_f32 v[186:187], v[186:187], v[230:231]
	v_pk_fma_f32 v[42:43], v[172:173], v[92:93], v[42:43]
	v_pk_mul_f32 v[172:173], v[172:173], v[232:233]
	v_pk_fma_f32 v[44:45], v[188:189], v[92:93], v[44:45]
	v_pk_mul_f32 v[188:189], v[188:189], v[232:233]
	v_pk_fma_f32 v[42:43], v[174:175], v[94:95], v[42:43]
	v_pk_mul_f32 v[174:175], v[174:175], v[234:235]
	v_pk_fma_f32 v[44:45], v[190:191], v[94:95], v[44:45]
	v_pk_mul_f32 v[190:191], v[190:191], v[234:235]
	v_add_f32_e32 v50, v42, v43
	v_add_f32_e32 v51, v44, v45
	v_mul_f32_e32 v36, s36, v36
	s_nop 0
	v_permlane32_swap_b32_e32 v50, v51
	v_add_f32_e32 v52, v50, v51
	s_nop 1
	v_permlane32_swap_b32_e32 v52, v36
	s_nop 1
	s_setprio 2
	v_mfma_f32_32x32x2_f32 v[128:143], v38, v52, v[128:143]
	ds_read_b128 v[64:67], v7 offset:1536
	ds_read_b128 v[56:59], v7 offset:1792
	ds_read_b128 v[68:71], v7 offset:1568
	ds_read_b128 v[60:63], v7 offset:1824
	ds_read_b128 v[72:75], v7 offset:1600
	ds_read_b128 v[212:215], v7 offset:1856
	ds_read_b128 v[76:79], v7 offset:1632
	ds_read_b128 v[216:219], v7 offset:1888
	ds_read_b128 v[80:83], v7 offset:1664
	v_mfma_f32_32x32x2_f32 v[144:159], v38, v36, v[144:159]
	ds_read_b128 v[220:223], v7 offset:1920
	ds_read_b128 v[84:87], v7 offset:1696
	ds_read_b128 v[224:227], v7 offset:1952
	ds_read_b128 v[88:91], v7 offset:1728
	ds_read_b128 v[228:231], v7 offset:1984
	ds_read_b128 v[92:95], v7 offset:1760
	ds_read_b128 v[232:235], v7 offset:2016
	ds_read_b32 v40, v8 offset:2048
	ds_read_b32 v41, v8 offset:2176
	v_mfma_f32_32x32x2_f32 v[160:175], v39, v52, v[160:175]
	ds_read_b32 v37, v9 offset:2560
	ds_read_b128 v[96:99], v7 offset:1280
	ds_read_b128 v[100:103], v7 offset:1312
	ds_read_b128 v[108:111], v7 offset:1344
	ds_read_b128 v[112:115], v7 offset:1376
	ds_read_b128 v[116:119], v7 offset:1408
	ds_read_b128 v[120:123], v7 offset:1440
	ds_read_b128 v[124:127], v7 offset:1472
	ds_read_b128 v[192:195], v7 offset:1504
	v_mfma_f32_32x32x2_f32 v[176:191], v39, v36, v[176:191]
	s_setprio 0
	s_waitcnt lgkmcnt(0)
; template <int NV, bool WITH_Y, int CH>
; __device__ __forceinline__ void scan_run(f32x2 (&S)[4][8], const unsigned char* oh  , LAS float* wl, float* yout  , int lane) {
;     ...
;         for (int s = 0; s < CH; ++s) {
;             const LAS float* sp = wl + s * 384 + cs16;
;             f32x4 a4[4], w4[4], b4[4], k4[4], r4[4], v4 = {0.f, 0.f, 0.f, 0.f};
; #pragma unroll
;             for (int q = 0; q < 4; ++q) a4[q] = *(const LAS f32x4*)(sp + q * 4);
; #pragma unroll
;             for (int q = 0; q < 4; ++q) { w4[q] = *(const LAS f32x4*)(sp + 64 + q * 4); b4[q] = *(const LAS f32x4*)(sp + 128 + q * 4); }
;             if (NV >= 5) {
; #pragma unroll
;                 for (int q = 0; q < 4; ++q) k4[q] = *(const LAS f32x4*)(sp + 192 + q * 4);
;                 v4 = *(const LAS f32x4*)(wl + s * 384 + 256 + rg4);
;             }
;             if (WITH_Y) {
; #pragma unroll
;                 for (int q = 0; q < 4; ++q) r4[q] = *(const LAS f32x4*)(sp + 320 + q * 4);
;             }
;             __builtin_amdgcn_sched_barrier(0);
;             float sa[4];
; #pragma unroll
;             for (int r = 0; r < 4; ++r) {
;                 f32x2 e0 = S[r][0] * (f32x2){a4[0][0], a4[0][1]}, e1 = S[r][1] * (f32x2){a4[0][2], a4[0][3]};
; #pragma unroll
;                 for (int q = 1; q < 4; ++q) { e0 += S[r][2 * q] * (f32x2){a4[q][0], a4[q][1]}; e1 += S[r][2 * q + 1] * (f32x2){a4[q][2], a4[q][3]}; }
;                 sa[r] = quad_allsum((e0[0] + e0[1]) + (e1[0] + e1[1]));
;             }
; #pragma unroll
;             for (int q = 0; q < 4; ++q) {
;                 const f32x2 wlo = {w4[q][0], w4[q][1]}, whi = {w4[q][2], w4[q][3]}, blo = {b4[q][0], b4[q][1]}, bhi = {b4[q][2], b4[q][3]};
;                 if (NV >= 5) {
;                     const f32x2 klo = {k4[q][0], k4[q][1]}, khi = {k4[q][2], k4[q][3]};
; #pragma unroll
;                     for (int r = 0; r < 4; ++r) {
;                         const f32x2 sa2 = {sa[r], sa[r]}, vi2 = {v4[r], v4[r]};
;                         S[r][2 * q] = S[r][2 * q] * wlo + (blo * sa2 + klo * vi2);
;                         S[r][2 * q + 1] = S[r][2 * q + 1] * whi + (bhi * sa2 + khi * vi2);
;                     }
;                 } else {
; #pragma unroll
;                     for (int r = 0; r < 4; ++r) {
;                         const f32x2 sa2 = {sa[r], sa[r]};
;                         S[r][2 * q] = S[r][2 * q] * wlo + blo * sa2;
	v_pk_mul_f32 v[42:43], v[128:129], v[64:65]
	v_pk_mul_f32 v[46:47], v[128:129], v[96:97]
	v_pk_mul_f32 v[128:129], v[128:129], v[56:57]
	v_pk_mul_f32 v[44:45], v[144:145], v[64:65]
	v_pk_mul_f32 v[48:49], v[144:145], v[96:97]
	v_pk_mul_f32 v[144:145], v[144:145], v[56:57]
	v_pk_fma_f32 v[42:43], v[130:131], v[66:67], v[42:43]
	v_pk_fma_f32 v[46:47], v[130:131], v[98:99], v[46:47]
	v_pk_mul_f32 v[130:131], v[130:131], v[58:59]
	v_pk_fma_f32 v[44:45], v[146:147], v[66:67], v[44:45]
	v_pk_fma_f32 v[48:49], v[146:147], v[98:99], v[48:49]
	v_pk_mul_f32 v[146:147], v[146:147], v[58:59]
	v_pk_fma_f32 v[42:43], v[132:133], v[68:69], v[42:43]
	v_pk_fma_f32 v[46:47], v[132:133], v[100:101], v[46:47]
	v_pk_mul_f32 v[132:133], v[132:133], v[60:61]
	v_pk_fma_f32 v[44:45], v[148:149], v[68:69], v[44:45]
	v_pk_fma_f32 v[48:49], v[148:149], v[100:101], v[48:49]
	v_pk_mul_f32 v[148:149], v[148:149], v[60:61]
	v_pk_fma_f32 v[42:43], v[134:135], v[70:71], v[42:43]
	v_pk_fma_f32 v[46:47], v[134:135], v[102:103], v[46:47]
	v_pk_mul_f32 v[134:135], v[134:135], v[62:63]
	v_pk_fma_f32 v[44:45], v[150:151], v[70:71], v[44:45]
	v_pk_fma_f32 v[48:49], v[150:151], v[102:103], v[48:49]
	v_pk_mul_f32 v[150:151], v[150:151], v[62:63]
	v_pk_fma_f32 v[42:43], v[136:137], v[72:73], v[42:43]
	v_pk_fma_f32 v[46:47], v[136:137], v[108:109], v[46:47]
	v_pk_mul_f32 v[136:137], v[136:137], v[212:213]
	v_pk_fma_f32 v[44:45], v[152:153], v[72:73], v[44:45]
	v_pk_fma_f32 v[48:49], v[152:153], v[108:109], v[48:49]
	v_pk_mul_f32 v[152:153], v[152:153], v[212:213]
	v_pk_fma_f32 v[42:43], v[138:139], v[74:75], v[42:43]
	v_pk_fma_f32 v[46:47], v[138:139], v[110:111], v[46:47]
	v_pk_mul_f32 v[138:139], v[138:139], v[214:215]
	v_pk_fma_f32 v[44:45], v[154:155], v[74:75], v[44:45]
	v_pk_fma_f32 v[48:49], v[154:155], v[110:111], v[48:49]
	v_pk_mul_f32 v[154:155], v[154:155], v[214:215]
	v_pk_fma_f32 v[42:43], v[140:141], v[76:77], v[42:43]
	v_pk_fma_f32 v[46:47], v[140:141], v[112:113], v[46:47]
	v_pk_mul_f32 v[140:141], v[140:141], v[216:217]
	v_pk_fma_f32 v[44:45], v[156:157], v[76:77], v[44:45]
	v_pk_fma_f32 v[48:49], v[156:157], v[112:113], v[48:49]
	v_pk_mul_f32 v[156:157], v[156:157], v[216:217]
	v_pk_fma_f32 v[42:43], v[142:143], v[78:79], v[42:43]
	v_pk_fma_f32 v[46:47], v[142:143], v[114:115], v[46:47]
	v_pk_mul_f32 v[142:143], v[142:143], v[218:219]
	v_pk_fma_f32 v[44:45], v[158:159], v[78:79], v[44:45]
	v_pk_fma_f32 v[48:49], v[158:159], v[114:115], v[48:49]
	v_pk_mul_f32 v[158:159], v[158:159], v[218:219]
	v_pk_fma_f32 v[42:43], v[160:161], v[80:81], v[42:43]
	v_pk_fma_f32 v[46:47], v[160:161], v[116:117], v[46:47]
	v_pk_mul_f32 v[160:161], v[160:161], v[220:221]
	v_pk_fma_f32 v[44:45], v[176:177], v[80:81], v[44:45]
	v_pk_fma_f32 v[48:49], v[176:177], v[116:117], v[48:49]
	v_pk_mul_f32 v[176:177], v[176:177], v[220:221]
	v_pk_fma_f32 v[42:43], v[162:163], v[82:83], v[42:43]
	v_pk_fma_f32 v[46:47], v[162:163], v[118:119], v[46:47]
	v_pk_mul_f32 v[162:163], v[162:163], v[222:223]
	v_pk_fma_f32 v[44:45], v[178:179], v[82:83], v[44:45]
	v_pk_fma_f32 v[48:49], v[178:179], v[118:119], v[48:49]
	v_pk_mul_f32 v[178:179], v[178:179], v[222:223]
	v_pk_fma_f32 v[42:43], v[164:165], v[84:85], v[42:43]
	v_pk_fma_f32 v[46:47], v[164:165], v[120:121], v[46:47]
	v_pk_mul_f32 v[164:165], v[164:165], v[224:225]
	v_pk_fma_f32 v[44:45], v[180:181], v[84:85], v[44:45]
	v_pk_fma_f32 v[48:49], v[180:181], v[120:121], v[48:49]
	v_pk_mul_f32 v[180:181], v[180:181], v[224:225]
	v_pk_fma_f32 v[42:43], v[166:167], v[86:87], v[42:43]
	v_pk_fma_f32 v[46:47], v[166:167], v[122:123], v[46:47]
	v_pk_mul_f32 v[166:167], v[166:167], v[226:227]
	v_pk_fma_f32 v[44:45], v[182:183], v[86:87], v[44:45]
	v_pk_fma_f32 v[48:49], v[182:183], v[122:123], v[48:49]
	v_pk_mul_f32 v[182:183], v[182:183], v[226:227]
	v_pk_fma_f32 v[42:43], v[168:169], v[88:89], v[42:43]
	v_pk_fma_f32 v[46:47], v[168:169], v[124:125], v[46:47]
	v_pk_mul_f32 v[168:169], v[168:169], v[228:229]
	v_pk_fma_f32 v[44:45], v[184:185], v[88:89], v[44:45]
	v_pk_fma_f32 v[48:49], v[184:185], v[124:125], v[48:49]
	v_pk_mul_f32 v[184:185], v[184:185], v[228:229]
	v_pk_fma_f32 v[42:43], v[170:171], v[90:91], v[42:43]
	v_pk_fma_f32 v[46:47], v[170:171], v[126:127], v[46:47]
	v_pk_mul_f32 v[170:171], v[170:171], v[230:231]
	v_pk_fma_f32 v[44:45], v[186:187], v[90:91], v[44:45]
	v_pk_fma_f32 v[48:49], v[186:187], v[126:127], v[48:49]
	v_pk_mul_f32 v[186:187], v[186:187], v[230:231]
	v_pk_fma_f32 v[42:43], v[172:173], v[92:93], v[42:43]
	v_pk_fma_f32 v[46:47], v[172:173], v[192:193], v[46:47]
	v_pk_mul_f32 v[172:173], v[172:173], v[232:233]
	v_pk_fma_f32 v[44:45], v[188:189], v[92:93], v[44:45]
	v_pk_fma_f32 v[48:49], v[188:189], v[192:193], v[48:49]
	v_pk_mul_f32 v[188:189], v[188:189], v[232:233]
	v_pk_fma_f32 v[42:43], v[174:175], v[94:95], v[42:43]
	v_pk_fma_f32 v[46:47], v[174:175], v[194:195], v[46:47]
	v_pk_mul_f32 v[174:175], v[174:175], v[234:235]
	v_pk_fma_f32 v[44:45], v[190:191], v[94:95], v[44:45]
	v_pk_fma_f32 v[48:49], v[190:191], v[194:195], v[48:49]
	v_pk_mul_f32 v[190:191], v[190:191], v[234:235]
	v_add_f32_e32 v50, v42, v43
	v_add_f32_e32 v51, v44, v45
	v_add_f32_e32 v54, v46, v47
	v_add_f32_e32 v55, v48, v49
	v_mul_f32_e32 v37, s36, v37
	v_permlane32_swap_b32_e32 v50, v51
	v_permlane32_swap_b32_e32 v54, v55
	v_add_f32_e32 v53, v50, v51
	v_add_f32_e32 v198, v54, v55
	s_nop 0
	v_permlane32_swap_b32_e32 v53, v37
	global_store_dword v[10:11], v198, off
	v_lshl_add_u64 v[10:11], v[10:11], 0, s[92:93]
	s_setprio 2
	v_mfma_f32_32x32x2_f32 v[128:143], v40, v53, v[128:143]
	ds_read_b128 v[64:67], v7 offset:3072
	ds_read_b128 v[56:59], v7 offset:3328
	ds_read_b128 v[68:71], v7 offset:3104
	ds_read_b128 v[60:63], v7 offset:3360
	ds_read_b128 v[72:75], v7 offset:3136
	ds_read_b128 v[212:215], v7 offset:3392
	ds_read_b128 v[76:79], v7 offset:3168
	ds_read_b128 v[216:219], v7 offset:3424
	ds_read_b128 v[80:83], v7 offset:3200
	v_mfma_f32_32x32x2_f32 v[144:159], v40, v37, v[144:159]
	ds_read_b128 v[220:223], v7 offset:3456
	ds_read_b128 v[84:87], v7 offset:3232
	ds_read_b128 v[224:227], v7 offset:3488
	ds_read_b128 v[88:91], v7 offset:3264
	ds_read_b128 v[228:231], v7 offset:3520
	ds_read_b128 v[92:95], v7 offset:3296
	ds_read_b128 v[232:235], v7 offset:3552
	ds_read_b32 v38, v8 offset:3584
	ds_read_b32 v39, v8 offset:3712
	v_mfma_f32_32x32x2_f32 v[160:175], v41, v53, v[160:175]
	ds_read_b32 v36, v9 offset:4096
	ds_read_b128 v[96:99], v7 offset:2816
	ds_read_b128 v[100:103], v7 offset:2848
	ds_read_b128 v[108:111], v7 offset:2880
	ds_read_b128 v[112:115], v7 offset:2912
	ds_read_b128 v[116:119], v7 offset:2944
	ds_read_b128 v[120:123], v7 offset:2976
	ds_read_b128 v[124:127], v7 offset:3008
	ds_read_b128 v[192:195], v7 offset:3040
	v_mfma_f32_32x32x2_f32 v[176:191], v41, v37, v[176:191]
	s_setprio 0
	s_waitcnt lgkmcnt(0)
; template <int NV, bool WITH_Y, int CH>
; __device__ __forceinline__ void scan_run(f32x2 (&S)[4][8], const unsigned char* oh  , LAS float* wl, float* yout  , int lane) {
;     ...
;         for (int s = 0; s < CH; ++s) {
;             const LAS float* sp = wl + s * 384 + cs16;
;             f32x4 a4[4], w4[4], b4[4], k4[4], r4[4], v4 = {0.f, 0.f, 0.f, 0.f};
; #pragma unroll
;             for (int q = 0; q < 4; ++q) a4[q] = *(const LAS f32x4*)(sp + q * 4);
; #pragma unroll
;             for (int q = 0; q < 4; ++q) { w4[q] = *(const LAS f32x4*)(sp + 64 + q * 4); b4[q] = *(const LAS f32x4*)(sp + 128 + q * 4); }
;             if (NV >= 5) {
; #pragma unroll
;                 for (int q = 0; q < 4; ++q) k4[q] = *(const LAS f32x4*)(sp + 192 + q * 4);
;                 v4 = *(const LAS f32x4*)(wl + s * 384 + 256 + rg4);
;             }
;             if (WITH_Y) {
; #pragma unroll
;                 for (int q = 0; q < 4; ++q) r4[q] = *(const LAS f32x4*)(sp + 320 + q * 4);
;             }
;             __builtin_amdgcn_sched_barrier(0);
;             float sa[4];
; #pragma unroll
;             for (int r = 0; r < 4; ++r) {
;                 f32x2 e0 = S[r][0] * (f32x2){a4[0][0], a4[0][1]}, e1 = S[r][1] * (f32x2){a4[0][2], a4[0][3]};
; #pragma unroll
;                 for (int q = 1; q < 4; ++q) { e0 += S[r][2 * q] * (f32x2){a4[q][0], a4[q][1]}; e1 += S[r][2 * q + 1] * (f32x2){a4[q][2], a4[q][3]}; }
;                 sa[r] = quad_allsum((e0[0] + e0[1]) + (e1[0] + e1[1]));
;             }
; #pragma unroll
;             for (int q = 0; q < 4; ++q) {
;                 const f32x2 wlo = {w4[q][0], w4[q][1]}, whi = {w4[q][2], w4[q][3]}, blo = {b4[q][0], b4[q][1]}, bhi = {b4[q][2], b4[q][3]};
;                 if (NV >= 5) {
;                     const f32x2 klo = {k4[q][0], k4[q][1]}, khi = {k4[q][2], k4[q][3]};
; #pragma unroll
;                     for (int r = 0; r < 4; ++r) {
;                         const f32x2 sa2 = {sa[r], sa[r]}, vi2 = {v4[r], v4[r]};
;                         S[r][2 * q] = S[r][2 * q] * wlo + (blo * sa2 + klo * vi2);
;                         S[r][2 * q + 1] = S[r][2 * q + 1] * whi + (bhi * sa2 + khi * vi2);
;                     }
;                 } else {
; #pragma unroll
;                     for (int r = 0; r < 4; ++r) {
;                         const f32x2 sa2 = {sa[r], sa[r]};
;                         S[r][2 * q] = S[r][2 * q] * wlo + blo * sa2;
	v_pk_mul_f32 v[42:43], v[128:129], v[64:65]
	v_pk_mul_f32 v[46:47], v[128:129], v[96:97]
	v_pk_mul_f32 v[128:129], v[128:129], v[56:57]
	v_pk_mul_f32 v[44:45], v[144:145], v[64:65]
	v_pk_mul_f32 v[48:49], v[144:145], v[96:97]
	v_pk_mul_f32 v[144:145], v[144:145], v[56:57]
	v_pk_fma_f32 v[42:43], v[130:131], v[66:67], v[42:43]
	v_pk_fma_f32 v[46:47], v[130:131], v[98:99], v[46:47]
	v_pk_mul_f32 v[130:131], v[130:131], v[58:59]
	v_pk_fma_f32 v[44:45], v[146:147], v[66:67], v[44:45]
	v_pk_fma_f32 v[48:49], v[146:147], v[98:99], v[48:49]
	v_pk_mul_f32 v[146:147], v[146:147], v[58:59]
	v_pk_fma_f32 v[42:43], v[132:133], v[68:69], v[42:43]
	v_pk_fma_f32 v[46:47], v[132:133], v[100:101], v[46:47]
	v_pk_mul_f32 v[132:133], v[132:133], v[60:61]
	v_pk_fma_f32 v[44:45], v[148:149], v[68:69], v[44:45]
	v_pk_fma_f32 v[48:49], v[148:149], v[100:101], v[48:49]
	v_pk_mul_f32 v[148:149], v[148:149], v[60:61]
	v_pk_fma_f32 v[42:43], v[134:135], v[70:71], v[42:43]
	v_pk_fma_f32 v[46:47], v[134:135], v[102:103], v[46:47]
	v_pk_mul_f32 v[134:135], v[134:135], v[62:63]
	v_pk_fma_f32 v[44:45], v[150:151], v[70:71], v[44:45]
	v_pk_fma_f32 v[48:49], v[150:151], v[102:103], v[48:49]
	v_pk_mul_f32 v[150:151], v[150:151], v[62:63]
	v_pk_fma_f32 v[42:43], v[136:137], v[72:73], v[42:43]
	v_pk_fma_f32 v[46:47], v[136:137], v[108:109], v[46:47]
	v_pk_mul_f32 v[136:137], v[136:137], v[212:213]
	v_pk_fma_f32 v[44:45], v[152:153], v[72:73], v[44:45]
	v_pk_fma_f32 v[48:49], v[152:153], v[108:109], v[48:49]
	v_pk_mul_f32 v[152:153], v[152:153], v[212:213]
	v_pk_fma_f32 v[42:43], v[138:139], v[74:75], v[42:43]
	v_pk_fma_f32 v[46:47], v[138:139], v[110:111], v[46:47]
	v_pk_mul_f32 v[138:139], v[138:139], v[214:215]
	v_pk_fma_f32 v[44:45], v[154:155], v[74:75], v[44:45]
	v_pk_fma_f32 v[48:49], v[154:155], v[110:111], v[48:49]
	v_pk_mul_f32 v[154:155], v[154:155], v[214:215]
	v_pk_fma_f32 v[42:43], v[140:141], v[76:77], v[42:43]
	v_pk_fma_f32 v[46:47], v[140:141], v[112:113], v[46:47]
	v_pk_mul_f32 v[140:141], v[140:141], v[216:217]
	v_pk_fma_f32 v[44:45], v[156:157], v[76:77], v[44:45]
	v_pk_fma_f32 v[48:49], v[156:157], v[112:113], v[48:49]
	v_pk_mul_f32 v[156:157], v[156:157], v[216:217]
	v_pk_fma_f32 v[42:43], v[142:143], v[78:79], v[42:43]
	v_pk_fma_f32 v[46:47], v[142:143], v[114:115], v[46:47]
	v_pk_mul_f32 v[142:143], v[142:143], v[218:219]
	v_pk_fma_f32 v[44:45], v[158:159], v[78:79], v[44:45]
	v_pk_fma_f32 v[48:49], v[158:159], v[114:115], v[48:49]
	v_pk_mul_f32 v[158:159], v[158:159], v[218:219]
	v_pk_fma_f32 v[42:43], v[160:161], v[80:81], v[42:43]
	v_pk_fma_f32 v[46:47], v[160:161], v[116:117], v[46:47]
	v_pk_mul_f32 v[160:161], v[160:161], v[220:221]
	v_pk_fma_f32 v[44:45], v[176:177], v[80:81], v[44:45]
	v_pk_fma_f32 v[48:49], v[176:177], v[116:117], v[48:49]
	v_pk_mul_f32 v[176:177], v[176:177], v[220:221]
	v_pk_fma_f32 v[42:43], v[162:163], v[82:83], v[42:43]
	v_pk_fma_f32 v[46:47], v[162:163], v[118:119], v[46:47]
	v_pk_mul_f32 v[162:163], v[162:163], v[222:223]
	v_pk_fma_f32 v[44:45], v[178:179], v[82:83], v[44:45]
	v_pk_fma_f32 v[48:49], v[178:179], v[118:119], v[48:49]
	v_pk_mul_f32 v[178:179], v[178:179], v[222:223]
	v_pk_fma_f32 v[42:43], v[164:165], v[84:85], v[42:43]
	v_pk_fma_f32 v[46:47], v[164:165], v[120:121], v[46:47]
	v_pk_mul_f32 v[164:165], v[164:165], v[224:225]
	v_pk_fma_f32 v[44:45], v[180:181], v[84:85], v[44:45]
	v_pk_fma_f32 v[48:49], v[180:181], v[120:121], v[48:49]
	v_pk_mul_f32 v[180:181], v[180:181], v[224:225]
	v_pk_fma_f32 v[42:43], v[166:167], v[86:87], v[42:43]
	v_pk_fma_f32 v[46:47], v[166:167], v[122:123], v[46:47]
	v_pk_mul_f32 v[166:167], v[166:167], v[226:227]
	v_pk_fma_f32 v[44:45], v[182:183], v[86:87], v[44:45]
	v_pk_fma_f32 v[48:49], v[182:183], v[122:123], v[48:49]
	v_pk_mul_f32 v[182:183], v[182:183], v[226:227]
	v_pk_fma_f32 v[42:43], v[168:169], v[88:89], v[42:43]
	v_pk_fma_f32 v[46:47], v[168:169], v[124:125], v[46:47]
	v_pk_mul_f32 v[168:169], v[168:169], v[228:229]
	v_pk_fma_f32 v[44:45], v[184:185], v[88:89], v[44:45]
	v_pk_fma_f32 v[48:49], v[184:185], v[124:125], v[48:49]
	v_pk_mul_f32 v[184:185], v[184:185], v[228:229]
	v_pk_fma_f32 v[42:43], v[170:171], v[90:91], v[42:43]
	v_pk_fma_f32 v[46:47], v[170:171], v[126:127], v[46:47]
	v_pk_mul_f32 v[170:171], v[170:171], v[230:231]
	v_pk_fma_f32 v[44:45], v[186:187], v[90:91], v[44:45]
	v_pk_fma_f32 v[48:49], v[186:187], v[126:127], v[48:49]
	v_pk_mul_f32 v[186:187], v[186:187], v[230:231]
	v_pk_fma_f32 v[42:43], v[172:173], v[92:93], v[42:43]
	v_pk_fma_f32 v[46:47], v[172:173], v[192:193], v[46:47]
	v_pk_mul_f32 v[172:173], v[172:173], v[232:233]
	v_pk_fma_f32 v[44:45], v[188:189], v[92:93], v[44:45]
	v_pk_fma_f32 v[48:49], v[188:189], v[192:193], v[48:49]
	v_pk_mul_f32 v[188:189], v[188:189], v[232:233]
	v_pk_fma_f32 v[42:43], v[174:175], v[94:95], v[42:43]
	v_pk_fma_f32 v[46:47], v[174:175], v[194:195], v[46:47]
	v_pk_mul_f32 v[174:175], v[174:175], v[234:235]
	v_pk_fma_f32 v[44:45], v[190:191], v[94:95], v[44:45]
	v_pk_fma_f32 v[48:49], v[190:191], v[194:195], v[48:49]
	v_pk_mul_f32 v[190:191], v[190:191], v[234:235]
	v_add_f32_e32 v50, v42, v43
	v_add_f32_e32 v51, v44, v45
	v_add_f32_e32 v54, v46, v47
	v_add_f32_e32 v55, v48, v49
	v_mul_f32_e32 v36, s36, v36
	v_permlane32_swap_b32_e32 v50, v51
	v_permlane32_swap_b32_e32 v54, v55
	v_add_f32_e32 v52, v50, v51
	v_add_f32_e32 v198, v54, v55
	s_nop 0
	v_permlane32_swap_b32_e32 v52, v36
	global_store_dword v[10:11], v198, off
	v_lshl_add_u64 v[10:11], v[10:11], 0, s[92:93]
	s_setprio 2
	v_mfma_f32_32x32x2_f32 v[128:143], v38, v52, v[128:143]
	ds_read_b128 v[64:67], v7 offset:4608
	ds_read_b128 v[56:59], v7 offset:4864
	ds_read_b128 v[68:71], v7 offset:4640
	ds_read_b128 v[60:63], v7 offset:4896
	ds_read_b128 v[72:75], v7 offset:4672
	ds_read_b128 v[212:215], v7 offset:4928
	ds_read_b128 v[76:79], v7 offset:4704
	ds_read_b128 v[216:219], v7 offset:4960
	ds_read_b128 v[80:83], v7 offset:4736
	v_mfma_f32_32x32x2_f32 v[144:159], v38, v36, v[144:159]
	ds_read_b128 v[220:223], v7 offset:4992
	ds_read_b128 v[84:87], v7 offset:4768
	ds_read_b128 v[224:227], v7 offset:5024
	ds_read_b128 v[88:91], v7 offset:4800
	ds_read_b128 v[228:231], v7 offset:5056
	ds_read_b128 v[92:95], v7 offset:4832
	ds_read_b128 v[232:235], v7 offset:5088
	ds_read_b32 v40, v8 offset:5120
	ds_read_b32 v41, v8 offset:5248
	v_mfma_f32_32x32x2_f32 v[160:175], v39, v52, v[160:175]
	ds_read_b32 v37, v9 offset:5632
	ds_read_b128 v[96:99], v7 offset:4352
	ds_read_b128 v[100:103], v7 offset:4384
	ds_read_b128 v[108:111], v7 offset:4416
	ds_read_b128 v[112:115], v7 offset:4448
	ds_read_b128 v[116:119], v7 offset:4480
	ds_read_b128 v[120:123], v7 offset:4512
	ds_read_b128 v[124:127], v7 offset:4544
	ds_read_b128 v[192:195], v7 offset:4576
	v_mfma_f32_32x32x2_f32 v[176:191], v39, v36, v[176:191]
	s_setprio 0
	s_waitcnt lgkmcnt(0)
; template <int NV, bool WITH_Y, int CH>
; __device__ __forceinline__ void scan_run(f32x2 (&S)[4][8], const unsigned char* oh  , LAS float* wl, float* yout  , int lane) {
;     ...
;         for (int s = 0; s < CH; ++s) {
;             const LAS float* sp = wl + s * 384 + cs16;
;             f32x4 a4[4], w4[4], b4[4], k4[4], r4[4], v4 = {0.f, 0.f, 0.f, 0.f};
; #pragma unroll
;             for (int q = 0; q < 4; ++q) a4[q] = *(const LAS f32x4*)(sp + q * 4);
; #pragma unroll
;             for (int q = 0; q < 4; ++q) { w4[q] = *(const LAS f32x4*)(sp + 64 + q * 4); b4[q] = *(const LAS f32x4*)(sp + 128 + q * 4); }
;             if (NV >= 5) {
; #pragma unroll
;                 for (int q = 0; q < 4; ++q) k4[q] = *(const LAS f32x4*)(sp + 192 + q * 4);
;                 v4 = *(const LAS f32x4*)(wl + s * 384 + 256 + rg4);
;             }
;             if (WITH_Y) {
; #pragma unroll
;                 for (int q = 0; q < 4; ++q) r4[q] = *(const LAS f32x4*)(sp + 320 + q * 4);
;             }
;             __builtin_amdgcn_sched_barrier(0);
;             float sa[4];
; #pragma unroll
;             for (int r = 0; r < 4; ++r) {
;                 f32x2 e0 = S[r][0] * (f32x2){a4[0][0], a4[0][1]}, e1 = S[r][1] * (f32x2){a4[0][2], a4[0][3]};
; #pragma unroll
;                 for (int q = 1; q < 4; ++q) { e0 += S[r][2 * q] * (f32x2){a4[q][0], a4[q][1]}; e1 += S[r][2 * q + 1] * (f32x2){a4[q][2], a4[q][3]}; }
;                 sa[r] = quad_allsum((e0[0] + e0[1]) + (e1[0] + e1[1]));
;             }
; #pragma unroll
;             for (int q = 0; q < 4; ++q) {
;                 const f32x2 wlo = {w4[q][0], w4[q][1]}, whi = {w4[q][2], w4[q][3]}, blo = {b4[q][0], b4[q][1]}, bhi = {b4[q][2], b4[q][3]};
;                 if (NV >= 5) {
;                     const f32x2 klo = {k4[q][0], k4[q][1]}, khi = {k4[q][2], k4[q][3]};
; #pragma unroll
;                     for (int r = 0; r < 4; ++r) {
;                         const f32x2 sa2 = {sa[r], sa[r]}, vi2 = {v4[r], v4[r]};
;                         S[r][2 * q] = S[r][2 * q] * wlo + (blo * sa2 + klo * vi2);
;                         S[r][2 * q + 1] = S[r][2 * q + 1] * whi + (bhi * sa2 + khi * vi2);
;                     }
;                 } else {
; #pragma unroll
;                     for (int r = 0; r < 4; ++r) {
;                         const f32x2 sa2 = {sa[r], sa[r]};
;                         S[r][2 * q] = S[r][2 * q] * wlo + blo * sa2;
	v_pk_mul_f32 v[42:43], v[128:129], v[64:65]
	v_pk_mul_f32 v[46:47], v[128:129], v[96:97]
	v_pk_mul_f32 v[128:129], v[128:129], v[56:57]
	v_pk_mul_f32 v[44:45], v[144:145], v[64:65]
	v_pk_mul_f32 v[48:49], v[144:145], v[96:97]
	v_pk_mul_f32 v[144:145], v[144:145], v[56:57]
	v_pk_fma_f32 v[42:43], v[130:131], v[66:67], v[42:43]
	v_pk_fma_f32 v[46:47], v[130:131], v[98:99], v[46:47]
	v_pk_mul_f32 v[130:131], v[130:131], v[58:59]
	v_pk_fma_f32 v[44:45], v[146:147], v[66:67], v[44:45]
	v_pk_fma_f32 v[48:49], v[146:147], v[98:99], v[48:49]
	v_pk_mul_f32 v[146:147], v[146:147], v[58:59]
	v_pk_fma_f32 v[42:43], v[132:133], v[68:69], v[42:43]
	v_pk_fma_f32 v[46:47], v[132:133], v[100:101], v[46:47]
	v_pk_mul_f32 v[132:133], v[132:133], v[60:61]
	v_pk_fma_f32 v[44:45], v[148:149], v[68:69], v[44:45]
	v_pk_fma_f32 v[48:49], v[148:149], v[100:101], v[48:49]
	v_pk_mul_f32 v[148:149], v[148:149], v[60:61]
	v_pk_fma_f32 v[42:43], v[134:135], v[70:71], v[42:43]
	v_pk_fma_f32 v[46:47], v[134:135], v[102:103], v[46:47]
	v_pk_mul_f32 v[134:135], v[134:135], v[62:63]
	v_pk_fma_f32 v[44:45], v[150:151], v[70:71], v[44:45]
	v_pk_fma_f32 v[48:49], v[150:151], v[102:103], v[48:49]
	v_pk_mul_f32 v[150:151], v[150:151], v[62:63]
	v_pk_fma_f32 v[42:43], v[136:137], v[72:73], v[42:43]
	v_pk_fma_f32 v[46:47], v[136:137], v[108:109], v[46:47]
	v_pk_mul_f32 v[136:137], v[136:137], v[212:213]
	v_pk_fma_f32 v[44:45], v[152:153], v[72:73], v[44:45]
	v_pk_fma_f32 v[48:49], v[152:153], v[108:109], v[48:49]
	v_pk_mul_f32 v[152:153], v[152:153], v[212:213]
	v_pk_fma_f32 v[42:43], v[138:139], v[74:75], v[42:43]
	v_pk_fma_f32 v[46:47], v[138:139], v[110:111], v[46:47]
	v_pk_mul_f32 v[138:139], v[138:139], v[214:215]
	v_pk_fma_f32 v[44:45], v[154:155], v[74:75], v[44:45]
	v_pk_fma_f32 v[48:49], v[154:155], v[110:111], v[48:49]
	v_pk_mul_f32 v[154:155], v[154:155], v[214:215]
	v_pk_fma_f32 v[42:43], v[140:141], v[76:77], v[42:43]
	v_pk_fma_f32 v[46:47], v[140:141], v[112:113], v[46:47]
	v_pk_mul_f32 v[140:141], v[140:141], v[216:217]
	v_pk_fma_f32 v[44:45], v[156:157], v[76:77], v[44:45]
	v_pk_fma_f32 v[48:49], v[156:157], v[112:113], v[48:49]
	v_pk_mul_f32 v[156:157], v[156:157], v[216:217]
	v_pk_fma_f32 v[42:43], v[142:143], v[78:79], v[42:43]
	v_pk_fma_f32 v[46:47], v[142:143], v[114:115], v[46:47]
	v_pk_mul_f32 v[142:143], v[142:143], v[218:219]
	v_pk_fma_f32 v[44:45], v[158:159], v[78:79], v[44:45]
	v_pk_fma_f32 v[48:49], v[158:159], v[114:115], v[48:49]
	v_pk_mul_f32 v[158:159], v[158:159], v[218:219]
	v_pk_fma_f32 v[42:43], v[160:161], v[80:81], v[42:43]
	v_pk_fma_f32 v[46:47], v[160:161], v[116:117], v[46:47]
	v_pk_mul_f32 v[160:161], v[160:161], v[220:221]
	v_pk_fma_f32 v[44:45], v[176:177], v[80:81], v[44:45]
	v_pk_fma_f32 v[48:49], v[176:177], v[116:117], v[48:49]
	v_pk_mul_f32 v[176:177], v[176:177], v[220:221]
	v_pk_fma_f32 v[42:43], v[162:163], v[82:83], v[42:43]
	v_pk_fma_f32 v[46:47], v[162:163], v[118:119], v[46:47]
	v_pk_mul_f32 v[162:163], v[162:163], v[222:223]
	v_pk_fma_f32 v[44:45], v[178:179], v[82:83], v[44:45]
	v_pk_fma_f32 v[48:49], v[178:179], v[118:119], v[48:49]
	v_pk_mul_f32 v[178:179], v[178:179], v[222:223]
	v_pk_fma_f32 v[42:43], v[164:165], v[84:85], v[42:43]
	v_pk_fma_f32 v[46:47], v[164:165], v[120:121], v[46:47]
	v_pk_mul_f32 v[164:165], v[164:165], v[224:225]
	v_pk_fma_f32 v[44:45], v[180:181], v[84:85], v[44:45]
	v_pk_fma_f32 v[48:49], v[180:181], v[120:121], v[48:49]
	v_pk_mul_f32 v[180:181], v[180:181], v[224:225]
	v_pk_fma_f32 v[42:43], v[166:167], v[86:87], v[42:43]
	v_pk_fma_f32 v[46:47], v[166:167], v[122:123], v[46:47]
	v_pk_mul_f32 v[166:167], v[166:167], v[226:227]
	v_pk_fma_f32 v[44:45], v[182:183], v[86:87], v[44:45]
	v_pk_fma_f32 v[48:49], v[182:183], v[122:123], v[48:49]
	v_pk_mul_f32 v[182:183], v[182:183], v[226:227]
	v_pk_fma_f32 v[42:43], v[168:169], v[88:89], v[42:43]
	v_pk_fma_f32 v[46:47], v[168:169], v[124:125], v[46:47]
	v_pk_mul_f32 v[168:169], v[168:169], v[228:229]
	v_pk_fma_f32 v[44:45], v[184:185], v[88:89], v[44:45]
	v_pk_fma_f32 v[48:49], v[184:185], v[124:125], v[48:49]
	v_pk_mul_f32 v[184:185], v[184:185], v[228:229]
	v_pk_fma_f32 v[42:43], v[170:171], v[90:91], v[42:43]
	v_pk_fma_f32 v[46:47], v[170:171], v[126:127], v[46:47]
	v_pk_mul_f32 v[170:171], v[170:171], v[230:231]
	v_pk_fma_f32 v[44:45], v[186:187], v[90:91], v[44:45]
	v_pk_fma_f32 v[48:49], v[186:187], v[126:127], v[48:49]
	v_pk_mul_f32 v[186:187], v[186:187], v[230:231]
	v_pk_fma_f32 v[42:43], v[172:173], v[92:93], v[42:43]
	v_pk_fma_f32 v[46:47], v[172:173], v[192:193], v[46:47]
	v_pk_mul_f32 v[172:173], v[172:173], v[232:233]
	v_pk_fma_f32 v[44:45], v[188:189], v[92:93], v[44:45]
	v_pk_fma_f32 v[48:49], v[188:189], v[192:193], v[48:49]
	v_pk_mul_f32 v[188:189], v[188:189], v[232:233]
	v_pk_fma_f32 v[42:43], v[174:175], v[94:95], v[42:43]
	v_pk_fma_f32 v[46:47], v[174:175], v[194:195], v[46:47]
	v_pk_mul_f32 v[174:175], v[174:175], v[234:235]
	v_pk_fma_f32 v[44:45], v[190:191], v[94:95], v[44:45]
	v_pk_fma_f32 v[48:49], v[190:191], v[194:195], v[48:49]
	v_pk_mul_f32 v[190:191], v[190:191], v[234:235]
	v_add_f32_e32 v50, v42, v43
	v_add_f32_e32 v51, v44, v45
	v_add_f32_e32 v54, v46, v47
	v_add_f32_e32 v55, v48, v49
	v_mul_f32_e32 v37, s36, v37
	v_permlane32_swap_b32_e32 v50, v51
	v_permlane32_swap_b32_e32 v54, v55
	v_add_f32_e32 v53, v50, v51
	v_add_f32_e32 v198, v54, v55
	s_nop 0
	v_permlane32_swap_b32_e32 v53, v37
	global_store_dword v[10:11], v198, off
	v_lshl_add_u64 v[10:11], v[10:11], 0, s[92:93]
	s_setprio 2
	v_mfma_f32_32x32x2_f32 v[128:143], v40, v53, v[128:143]
	ds_read_b128 v[96:99], v7 offset:5888
	ds_read_b128 v[100:103], v7 offset:5920
	ds_read_b128 v[108:111], v7 offset:5952
	v_mfma_f32_32x32x2_f32 v[144:159], v40, v37, v[144:159]
	ds_read_b128 v[112:115], v7 offset:5984
	ds_read_b128 v[116:119], v7 offset:6016
	ds_read_b128 v[120:123], v7 offset:6048
	v_mfma_f32_32x32x2_f32 v[160:175], v41, v53, v[160:175]
	ds_read_b128 v[124:127], v7 offset:6080
	ds_read_b128 v[192:195], v7 offset:6112
	v_mfma_f32_32x32x2_f32 v[176:191], v41, v37, v[176:191]
	s_setprio 0
	s_nop 15
	s_waitcnt lgkmcnt(0)
; #define LAS __attribute__((address_space(3)))
; template <int NV, bool WITH_Y, int CH>
; __device__ __forceinline__ void scan_run(f32x2 (&S)[4][8], const unsigned char* oh  , LAS float* wl, float* yout  , int lane) {
;     ...
;             if (WITH_Y) {
;                 float y[4];
; #pragma unroll
;                 for (int r = 0; r < 4; ++r) {
;                     f32x2 e0 = S[r][0] * (f32x2){r4[0][0], r4[0][1]}, e1 = S[r][1] * (f32x2){r4[0][2], r4[0][3]};
; #pragma unroll
;                     for (int q = 1; q < 4; ++q) { e0 += S[r][2 * q] * (f32x2){r4[q][0], r4[q][1]}; e1 += S[r][2 * q + 1] * (f32x2){r4[q][2], r4[q][3]}; }
;                     y[r] = quad_allsum((e0[0] + e0[1]) + (e1[0] + e1[1]));
;                 }
;                 const int cs = lane & 3;
;                 const float ysel = cs == 0 ? y[0] : (cs == 1 ? y[1] : (cs == 2 ? y[2] : y[3]));
;                 yout[(size_t)(c * CH + s) * RW + lane] = ysel;
;             }
;         }
;         asm volatile("s_waitcnt lgkmcnt(0)" ::: "memory");
;     }
; }
; __device__ __forceinline__ void phase_scan1(const Params& p, const Lt& lt, unsigned char* lds) {
;     const int tid = lt.tid, w = __builtin_amdgcn_readfirstlane(tid >> 6), G = gridDim.x;
;     LAS float* wl = (LAS float*)((LAS unsigned char*)lds) + w * (CHMAX * 384);
;     const unsigned char* opnd = p.ws + WS_OPND;
;     float* TG = (float*)(p.ws + WS_TG); float* LG = (float*)(p.ws + WS_LG);
;     const int nslot = (2 * NH * NSEG + G - 1) / G;
; #pragma unroll 1
;     for (int j = w; j < nslot; j += 8) {
;         int lane = tid & 63; asm volatile("" : "+v"(lane));
;         const int kind = (j ^ (j >> 3)) & 1;
;         const int rank = j >> 1;
;         const int pair = rank * G + lt.bid;
;         if (pair >= NH * NSEG) continue;
;         const int h = pair / NSEG, g = pair % NSEG, row0 = (lane >> 2) * 4, col0 = (lane & 3) * 16;
;         f32x2 S[4][8];
;         const unsigned char* oh = opnd + (size_t)g * SEGLEN * OPTB + h * OPB;
;         float* dst = (kind == 0 ? TG : LG) + (size_t)(h * NSEG + g) * 4096 + row0 * 64 + col0;
;         if (kind == 0) {
; #pragma unroll
;             for (int r = 0; r < 4; ++r)
; #pragma unroll
;                 for (int q = 0; q < 8; ++q) S[r][q] = (f32x2){(row0 + r == col0 + 2 * q) ? 1.f : 0.f, (row0 + r == col0 + 2 * q + 1) ? 1.f : 0.f};
	v_pk_mul_f32 v[46:47], v[128:129], v[96:97]
	v_pk_mul_f32 v[42:43], v[144:145], v[96:97]
	v_pk_mul_f32 v[48:49], v[130:131], v[98:99]
	v_pk_mul_f32 v[44:45], v[146:147], v[98:99]
	v_pk_fma_f32 v[46:47], v[132:133], v[100:101], v[46:47]
	v_pk_fma_f32 v[42:43], v[148:149], v[100:101], v[42:43]
	v_pk_fma_f32 v[48:49], v[134:135], v[102:103], v[48:49]
	v_pk_fma_f32 v[44:45], v[150:151], v[102:103], v[44:45]
	v_pk_fma_f32 v[46:47], v[136:137], v[108:109], v[46:47]
	v_pk_fma_f32 v[42:43], v[152:153], v[108:109], v[42:43]
	v_pk_fma_f32 v[48:49], v[138:139], v[110:111], v[48:49]
	v_pk_fma_f32 v[44:45], v[154:155], v[110:111], v[44:45]
	v_pk_fma_f32 v[46:47], v[140:141], v[112:113], v[46:47]
	v_pk_fma_f32 v[42:43], v[156:157], v[112:113], v[42:43]
	v_pk_fma_f32 v[48:49], v[142:143], v[114:115], v[48:49]
	v_pk_fma_f32 v[44:45], v[158:159], v[114:115], v[44:45]
	v_pk_fma_f32 v[46:47], v[160:161], v[116:117], v[46:47]
	v_pk_fma_f32 v[42:43], v[176:177], v[116:117], v[42:43]
	v_pk_fma_f32 v[48:49], v[162:163], v[118:119], v[48:49]
	v_pk_fma_f32 v[44:45], v[178:179], v[118:119], v[44:45]
	v_pk_fma_f32 v[46:47], v[164:165], v[120:121], v[46:47]
	v_pk_fma_f32 v[42:43], v[180:181], v[120:121], v[42:43]
	v_pk_fma_f32 v[48:49], v[166:167], v[122:123], v[48:49]
	v_pk_fma_f32 v[44:45], v[182:183], v[122:123], v[44:45]
	v_pk_fma_f32 v[46:47], v[168:169], v[124:125], v[46:47]
	v_pk_fma_f32 v[42:43], v[184:185], v[124:125], v[42:43]
	v_pk_fma_f32 v[48:49], v[170:171], v[126:127], v[48:49]
	v_pk_fma_f32 v[44:45], v[186:187], v[126:127], v[44:45]
	v_pk_fma_f32 v[46:47], v[172:173], v[192:193], v[46:47]
	v_pk_fma_f32 v[42:43], v[188:189], v[192:193], v[42:43]
	v_pk_fma_f32 v[48:49], v[174:175], v[194:195], v[48:49]
	v_pk_fma_f32 v[44:45], v[190:191], v[194:195], v[44:45]
	v_pk_add_f32 v[46:47], v[46:47], v[48:49]
	v_pk_add_f32 v[42:43], v[42:43], v[44:45]
	s_nop 0
	v_add_f32_e32 v54, v46, v47
	v_add_f32_e32 v55, v42, v43
	s_nop 1
	v_permlane32_swap_b32_e32 v54, v55
	v_add_f32_e32 v198, v54, v55
	global_store_dword v[10:11], v198, off
	v_lshl_add_u64 v[10:11], v[10:11], 0, s[92:93]
	s_add_i32 s51, s51, 1
	s_waitcnt vmcnt(4)
	s_cmp_eq_u32 s51, 16
	s_cbranch_scc0 .Lscan_chunk
	s_and_b64 s[0:1], exec, s[28:29]
	s_mov_b32 s0, 0x2d7a0000
	s_cselect_b32 s0, s0, 0x2efa0000
	s_add_u32 s4, s62, s0
	s_addc_u32 s5, s63, 0
	s_lshl_b32 s0, s47, 7
	s_add_i32 s0, s0, s48
	s_ashr_i32 s1, s0, 31
	s_lshl_b64 s[0:1], s[0:1], 14
	s_add_u32 s0, s4, s0
	s_addc_u32 s1, s5, s1
	v_lshlrev_b32_e32 v0, 8, v206
	v_lshl_add_u32 v0, v207, 4, v0
	v_mov_b32_e32 v1, 0
	v_lshl_add_u64 v[32:33], s[0:1], 0, v[0:1]
	v_add_co_u32_e32 v34, vcc, s71, v32
	s_nop 1
	v_addc_co_u32_e32 v35, vcc, 0, v33, vcc
	global_store_dwordx4 v[32:33], v[128:131], off
	global_store_dwordx4 v[32:33], v[132:135], off offset:32
	global_store_dwordx4 v[32:33], v[136:139], off offset:64
	global_store_dwordx4 v[32:33], v[140:143], off offset:96
	global_store_dwordx4 v[32:33], v[160:163], off offset:128
	global_store_dwordx4 v[32:33], v[164:167], off offset:160
	global_store_dwordx4 v[32:33], v[168:171], off offset:192
	global_store_dwordx4 v[32:33], v[172:175], off offset:224
	global_store_dwordx4 v[34:35], v[144:147], off
	global_store_dwordx4 v[34:35], v[148:151], off offset:32
	global_store_dwordx4 v[34:35], v[152:155], off offset:64
	global_store_dwordx4 v[34:35], v[156:159], off offset:96
	global_store_dwordx4 v[34:35], v[176:179], off offset:128
	global_store_dwordx4 v[34:35], v[180:183], off offset:160
	global_store_dwordx4 v[34:35], v[184:187], off offset:192
	global_store_dwordx4 v[34:35], v[188:191], off offset:224
	s_branch .LBB0_264
